# nt (streaming) hint on the x1 row loads of P6 and the f32 x residual loads of the P5 epilogue (both read once, long after they were written)
# speedup vs baseline: 1.0220x; 1.0039x over previous
; __device__ __forceinline__ unsigned cvt_pk_bf16(float lo, float hi) { unsigned r; asm("v_cvt_pk_bf16_f32 %0, %1, %2" : "=v"(r) : "v"(lo), "v"(hi)); return r; }
;     __device__ __forceinline__ void epi(Acc& acc, const Unit& u, int wr, int wc, int fr, int fq) const {
;     ...
;         if (u.kind == 0) {
;             const int b16 = u.pm >> 4;
; #pragma unroll
;             for (int ai = 0; ai < 2; ++ai) {
;                 f32x4 gv[2][2];
; #pragma unroll
;                 for (int bj = 0; bj < 2; ++bj)
; #pragma unroll
;                     for (int n = 0; n < 2; ++n) gv[bj][n] = *(const f32x4*)(gate + (size_t)b16 * 6144 + u.pn * 256 + bj * 128 + wc * 32 + fq * 8 + n * 4);
; #pragma unroll
;                 for (int m = 0; m < 4; ++m) { const int row = u.pm * 256 + ai * 128 + rl0 + m * 16;
; #pragma unroll
;                     for (int bj = 0; bj < 2; ++bj) { const int col = u.pn * 256 + bj * 128 + wc * 32 + fq * 8;
;                         if constexpr (MODE == 0) {
;                             const float* bp = xp + (size_t)row * DM;
;                             const f32x4 r0 = *(const f32x4*)(bp + col) + gv[bj][0] * acc[ai][bj][m][0], r1 = *(const f32x4*)(bp + col + 4) + gv[bj][1] * acc[ai][bj][m][1];
;                             u32x4 w; w.x = cvt_pk_bf16(r0[0], r0[1]); w.y = cvt_pk_bf16(r0[2], r0[3]); w.z = cvt_pk_bf16(r1[0], r1[1]); w.w = cvt_pk_bf16(r1[2], r1[3]);
;                             *(u32x4*)(X1 + (size_t)row * DM + col) = w;
.LBB0_1044:
	s_ashr_i32 s10, s52, 4
	s_mul_hi_i32 s11, s10, 0x6000
	s_mulk_i32 s10, 0x6000
	s_add_u32 s43, s26, s10
	s_addc_u32 s45, s27, s11
	s_lshl_b32 s10, s54, 8
	s_ashr_i32 s11, s10, 31
	s_lshl_b64 s[46:47], s[10:11], 2
	s_add_u32 s11, s43, s46
	s_addc_u32 s43, s45, s47
	s_add_u32 s46, s11, s67
	v_lshlrev_b32_e32 v130, 3, v129
	s_addc_u32 s47, s43, 0
	v_lshl_add_u32 v156, s52, 8, v128
	s_or_b32 s10, s10, s53
	v_readlane_b32 s72, v238, 4
	v_ashrrev_i32_e32 v157, 31, v156
	v_add_u32_e32 v160, s10, v130
	v_readlane_b32 s73, v238, 5
	v_lshlrev_b64 v[128:129], 12, v[156:157]
	v_readlane_b32 s74, v238, 6
	v_readlane_b32 s75, v238, 7
	s_mov_b64 s[12:13], s[72:73]
	v_ashrrev_i32_e32 v161, 31, v160
	v_lshl_add_u64 v[128:129], s[12:13], 0, v[128:129]
	v_lshlrev_b64 v[158:159], 2, v[160:161]
	v_ashrrev_i32_e32 v131, 31, v130
	v_lshl_add_u64 v[178:179], v[128:129], 0, v[158:159]
	v_lshl_add_u64 v[162:163], v[130:131], 2, s[46:47]
	global_load_dwordx4 v[170:173], v[178:179], off nt
	global_load_dwordx4 v[140:143], v[162:163], off
	global_load_dwordx4 v[136:139], v[162:163], off offset:16
	global_load_dwordx4 v[174:177], v[178:179], off offset:16 nt
	v_lshlrev_b64 v[128:129], 11, v[156:157]
	v_lshl_add_u64 v[180:181], s[4:5], 0, v[128:129]
	v_lshlrev_b64 v[160:161], 1, v[160:161]
	v_lshl_add_u64 v[180:181], v[180:181], 0, v[160:161]
	global_load_dwordx4 v[128:131], v[162:163], off offset:528
	global_load_dwordx4 v[132:135], v[162:163], off offset:512
	v_readlane_b32 s76, v238, 8
	v_readlane_b32 s77, v238, 9
	v_readlane_b32 s78, v238, 10
	v_readlane_b32 s79, v238, 11
	v_readlane_b32 s80, v238, 12
	v_readlane_b32 s81, v238, 13
	v_readlane_b32 s82, v238, 14
	v_readlane_b32 s83, v238, 15
	v_readlane_b32 s84, v238, 16
	v_readlane_b32 s85, v238, 17
	v_readlane_b32 s86, v238, 18
	v_readlane_b32 s87, v238, 19
	s_mov_b64 s[14:15], s[74:75]
	s_waitcnt vmcnt(0)
	v_pk_fma_f32 v[124:125], v[124:125], v[140:141], v[170:171]
	v_pk_fma_f32 v[126:127], v[126:127], v[142:143], v[172:173]
	v_pk_fma_f32 v[170:171], v[122:123], v[138:139], v[176:177]
	v_pk_fma_f32 v[122:123], v[120:121], v[136:137], v[174:175]
	v_cvt_pk_bf16_f32 v120, v124, v125
	v_cvt_pk_bf16_f32 v121, v126, v127
	s_nop 0
	v_cvt_pk_bf16_f32 v122, v122, v123
	v_cvt_pk_bf16_f32 v123, v170, v171
	global_store_dwordx4 v[180:181], v[120:123], off
	global_load_dwordx4 v[120:123], v[178:179], off offset:512 nt
	s_nop 0
	global_load_dwordx4 v[124:127], v[178:179], off offset:528 nt
	v_add_u32_e32 v170, 16, v156
	v_ashrrev_i32_e32 v171, 31, v170
	v_lshlrev_b64 v[172:173], 12, v[170:171]
	v_lshl_add_u64 v[172:173], s[12:13], 0, v[172:173]
	v_lshl_add_u64 v[172:173], v[172:173], 0, v[158:159]
	s_waitcnt vmcnt(1)
	v_pk_fma_f32 v[116:117], v[116:117], v[132:133], v[120:121]
	s_waitcnt vmcnt(0)
	v_pk_fma_f32 v[120:121], v[114:115], v[130:131], v[126:127]
	v_pk_fma_f32 v[114:115], v[112:113], v[128:129], v[124:125]
	v_pk_fma_f32 v[118:119], v[118:119], v[134:135], v[122:123]
	v_cvt_pk_bf16_f32 v112, v116, v117
	v_cvt_pk_bf16_f32 v114, v114, v115
	v_cvt_pk_bf16_f32 v115, v120, v121
	v_lshlrev_b64 v[120:121], 11, v[170:171]
	v_cvt_pk_bf16_f32 v113, v118, v119
	global_store_dwordx4 v[180:181], v[112:115], off offset:256
	global_load_dwordx4 v[112:115], v[172:173], off nt
	s_nop 0
	global_load_dwordx4 v[116:119], v[172:173], off offset:16 nt
	v_lshl_add_u64 v[120:121], s[4:5], 0, v[120:121]
	v_lshl_add_u64 v[120:121], v[120:121], 0, v[160:161]
	s_waitcnt vmcnt(1)
	v_pk_fma_f32 v[108:109], v[108:109], v[140:141], v[112:113]
	s_waitcnt vmcnt(0)
	v_pk_fma_f32 v[112:113], v[106:107], v[138:139], v[118:119]
	v_pk_fma_f32 v[106:107], v[104:105], v[136:137], v[116:117]
	v_pk_fma_f32 v[110:111], v[110:111], v[142:143], v[114:115]
	v_cvt_pk_bf16_f32 v104, v108, v109
	v_cvt_pk_bf16_f32 v106, v106, v107
	v_cvt_pk_bf16_f32 v107, v112, v113
	v_add_u32_e32 v112, 32, v156
	v_cvt_pk_bf16_f32 v105, v110, v111
	global_store_dwordx4 v[120:121], v[104:107], off
	global_load_dwordx4 v[104:107], v[172:173], off offset:512 nt
	s_nop 0
	global_load_dwordx4 v[108:111], v[172:173], off offset:528 nt
	v_ashrrev_i32_e32 v113, 31, v112
	v_lshlrev_b64 v[114:115], 12, v[112:113]
	v_lshl_add_u64 v[114:115], s[12:13], 0, v[114:115]
	v_lshl_add_u64 v[114:115], v[114:115], 0, v[158:159]
	s_waitcnt vmcnt(1)
	v_pk_fma_f32 v[100:101], v[100:101], v[132:133], v[104:105]
	s_waitcnt vmcnt(0)
	v_pk_fma_f32 v[104:105], v[98:99], v[130:131], v[110:111]
	v_pk_fma_f32 v[98:99], v[96:97], v[128:129], v[108:109]
	v_pk_fma_f32 v[102:103], v[102:103], v[134:135], v[106:107]
	v_cvt_pk_bf16_f32 v96, v100, v101
	v_cvt_pk_bf16_f32 v98, v98, v99
	v_cvt_pk_bf16_f32 v99, v104, v105
	v_lshlrev_b64 v[104:105], 11, v[112:113]
	v_cvt_pk_bf16_f32 v97, v102, v103
	global_store_dwordx4 v[120:121], v[96:99], off offset:256
	global_load_dwordx4 v[96:99], v[114:115], off nt
	s_nop 0
	global_load_dwordx4 v[100:103], v[114:115], off offset:16 nt
	v_lshl_add_u64 v[104:105], s[4:5], 0, v[104:105]
	v_lshl_add_u64 v[104:105], v[104:105], 0, v[160:161]
	s_waitcnt vmcnt(1)
	v_pk_fma_f32 v[92:93], v[92:93], v[140:141], v[96:97]
	s_waitcnt vmcnt(0)
	v_pk_fma_f32 v[96:97], v[90:91], v[138:139], v[102:103]
	v_pk_fma_f32 v[90:91], v[88:89], v[136:137], v[100:101]
	v_pk_fma_f32 v[94:95], v[94:95], v[142:143], v[98:99]
	v_cvt_pk_bf16_f32 v88, v92, v93
	v_cvt_pk_bf16_f32 v90, v90, v91
	v_cvt_pk_bf16_f32 v91, v96, v97
	v_add_u32_e32 v96, 48, v156
	v_cvt_pk_bf16_f32 v89, v94, v95
	global_store_dwordx4 v[104:105], v[88:91], off
	global_load_dwordx4 v[88:91], v[114:115], off offset:512 nt
	s_nop 0
	global_load_dwordx4 v[92:95], v[114:115], off offset:528 nt
	v_ashrrev_i32_e32 v97, 31, v96
	v_lshlrev_b64 v[98:99], 12, v[96:97]
	v_lshl_add_u64 v[98:99], s[12:13], 0, v[98:99]
	v_lshl_add_u64 v[98:99], v[98:99], 0, v[158:159]
	s_waitcnt vmcnt(1)
; __device__ __forceinline__ unsigned cvt_pk_bf16(float lo, float hi) { unsigned r; asm("v_cvt_pk_bf16_f32 %0, %1, %2" : "=v"(r) : "v"(lo), "v"(hi)); return r; }
;     __device__ __forceinline__ void epi(Acc& acc, const Unit& u, int wr, int wc, int fr, int fq) const {
;     ...
;         if (u.kind == 0) {
;             const int b16 = u.pm >> 4;
; #pragma unroll
;             for (int ai = 0; ai < 2; ++ai) {
;                 f32x4 gv[2][2];
; #pragma unroll
;                 for (int bj = 0; bj < 2; ++bj)
; #pragma unroll
;                     for (int n = 0; n < 2; ++n) gv[bj][n] = *(const f32x4*)(gate + (size_t)b16 * 6144 + u.pn * 256 + bj * 128 + wc * 32 + fq * 8 + n * 4);
; #pragma unroll
;                 for (int m = 0; m < 4; ++m) { const int row = u.pm * 256 + ai * 128 + rl0 + m * 16;
; #pragma unroll
;                     for (int bj = 0; bj < 2; ++bj) { const int col = u.pn * 256 + bj * 128 + wc * 32 + fq * 8;
;                         if constexpr (MODE == 0) {
;                             const float* bp = xp + (size_t)row * DM;
;                             const f32x4 r0 = *(const f32x4*)(bp + col) + gv[bj][0] * acc[ai][bj][m][0], r1 = *(const f32x4*)(bp + col + 4) + gv[bj][1] * acc[ai][bj][m][1];
;                             u32x4 w; w.x = cvt_pk_bf16(r0[0], r0[1]); w.y = cvt_pk_bf16(r0[2], r0[3]); w.z = cvt_pk_bf16(r1[0], r1[1]); w.w = cvt_pk_bf16(r1[2], r1[3]);
;                             *(u32x4*)(X1 + (size_t)row * DM + col) = w;
	v_pk_fma_f32 v[84:85], v[84:85], v[132:133], v[88:89]
	s_waitcnt vmcnt(0)
	v_pk_fma_f32 v[88:89], v[82:83], v[130:131], v[94:95]
	v_pk_fma_f32 v[82:83], v[80:81], v[128:129], v[92:93]
	v_pk_fma_f32 v[86:87], v[86:87], v[134:135], v[90:91]
	v_cvt_pk_bf16_f32 v80, v84, v85
	v_cvt_pk_bf16_f32 v82, v82, v83
	v_cvt_pk_bf16_f32 v83, v88, v89
	v_lshlrev_b64 v[88:89], 11, v[96:97]
	v_cvt_pk_bf16_f32 v81, v86, v87
	global_store_dwordx4 v[104:105], v[80:83], off offset:256
	global_load_dwordx4 v[80:83], v[98:99], off nt
	s_nop 0
	global_load_dwordx4 v[84:87], v[98:99], off offset:16 nt
	v_lshl_add_u64 v[88:89], s[4:5], 0, v[88:89]
	v_lshl_add_u64 v[88:89], v[88:89], 0, v[160:161]
	v_add_u32_e32 v90, 0x80, v156
	v_ashrrev_i32_e32 v91, 31, v90
	s_waitcnt vmcnt(1)
	v_pk_fma_f32 v[76:77], v[76:77], v[140:141], v[80:81]
	s_waitcnt vmcnt(0)
	v_pk_fma_f32 v[80:81], v[74:75], v[138:139], v[86:87]
	v_pk_fma_f32 v[74:75], v[72:73], v[136:137], v[84:85]
	v_pk_fma_f32 v[78:79], v[78:79], v[142:143], v[82:83]
	v_cvt_pk_bf16_f32 v72, v76, v77
	v_cvt_pk_bf16_f32 v74, v74, v75
	v_cvt_pk_bf16_f32 v75, v80, v81
	v_lshlrev_b64 v[80:81], 12, v[90:91]
	v_cvt_pk_bf16_f32 v73, v78, v79
	global_store_dwordx4 v[88:89], v[72:75], off
	global_load_dwordx4 v[72:75], v[98:99], off offset:512 nt
	s_nop 0
	global_load_dwordx4 v[76:79], v[98:99], off offset:528 nt
	v_lshl_add_u64 v[80:81], s[12:13], 0, v[80:81]
	v_lshl_add_u64 v[92:93], v[80:81], 0, v[158:159]
	s_waitcnt vmcnt(1)
	v_pk_fma_f32 v[68:69], v[68:69], v[132:133], v[72:73]
	s_waitcnt vmcnt(0)
	v_pk_fma_f32 v[72:73], v[66:67], v[130:131], v[78:79]
	v_pk_fma_f32 v[66:67], v[64:65], v[128:129], v[76:77]
	v_pk_fma_f32 v[70:71], v[70:71], v[134:135], v[74:75]
	v_cvt_pk_bf16_f32 v64, v68, v69
	v_cvt_pk_bf16_f32 v66, v66, v67
	v_cvt_pk_bf16_f32 v67, v72, v73
	v_lshlrev_b64 v[72:73], 11, v[90:91]
	v_cvt_pk_bf16_f32 v65, v70, v71
	global_store_dwordx4 v[88:89], v[64:67], off offset:256
	global_load_dwordx4 v[80:83], v[92:93], off nt
	global_load_dwordx4 v[68:71], v[162:163], off
	s_nop 0
	global_load_dwordx4 v[64:67], v[162:163], off offset:16
	global_load_dwordx4 v[84:87], v[92:93], off offset:16 nt
	v_lshl_add_u64 v[72:73], s[4:5], 0, v[72:73]
	v_lshl_add_u64 v[88:89], v[72:73], 0, v[160:161]
	global_load_dwordx4 v[72:75], v[162:163], off offset:528
	global_load_dwordx4 v[76:79], v[162:163], off offset:512
	s_waitcnt vmcnt(4)
	v_pk_fma_f32 v[60:61], v[60:61], v[68:69], v[80:81]
	v_pk_fma_f32 v[62:63], v[62:63], v[70:71], v[82:83]
	s_waitcnt vmcnt(2)
	v_pk_fma_f32 v[80:81], v[58:59], v[66:67], v[86:87]
	v_pk_fma_f32 v[58:59], v[56:57], v[64:65], v[84:85]
	v_cvt_pk_bf16_f32 v56, v60, v61
	v_cvt_pk_bf16_f32 v57, v62, v63
	s_nop 0
	v_cvt_pk_bf16_f32 v58, v58, v59
	v_cvt_pk_bf16_f32 v59, v80, v81
	global_store_dwordx4 v[88:89], v[56:59], off
	global_load_dwordx4 v[56:59], v[92:93], off offset:512 nt
	s_nop 0
	global_load_dwordx4 v[60:63], v[92:93], off offset:528 nt
	v_add_u32_e32 v80, 0x90, v156
	v_ashrrev_i32_e32 v81, 31, v80
	v_lshlrev_b64 v[82:83], 12, v[80:81]
	v_lshl_add_u64 v[82:83], s[12:13], 0, v[82:83]
	v_lshl_add_u64 v[82:83], v[82:83], 0, v[158:159]
	s_waitcnt vmcnt(1)
	v_pk_fma_f32 v[52:53], v[52:53], v[76:77], v[56:57]
	s_waitcnt vmcnt(0)
	v_pk_fma_f32 v[56:57], v[50:51], v[74:75], v[62:63]
	v_pk_fma_f32 v[50:51], v[48:49], v[72:73], v[60:61]
	v_pk_fma_f32 v[54:55], v[54:55], v[78:79], v[58:59]
	v_cvt_pk_bf16_f32 v48, v52, v53
	v_cvt_pk_bf16_f32 v50, v50, v51
	v_cvt_pk_bf16_f32 v51, v56, v57
	v_lshlrev_b64 v[56:57], 11, v[80:81]
	v_cvt_pk_bf16_f32 v49, v54, v55
	global_store_dwordx4 v[88:89], v[48:51], off offset:256
	global_load_dwordx4 v[48:51], v[82:83], off nt
	s_nop 0
	global_load_dwordx4 v[52:55], v[82:83], off offset:16 nt
	v_lshl_add_u64 v[56:57], s[4:5], 0, v[56:57]
	v_lshl_add_u64 v[56:57], v[56:57], 0, v[160:161]
	s_waitcnt vmcnt(1)
	v_pk_fma_f32 v[44:45], v[44:45], v[68:69], v[48:49]
	s_waitcnt vmcnt(0)
; __device__ __forceinline__ unsigned cvt_pk_bf16(float lo, float hi) { unsigned r; asm("v_cvt_pk_bf16_f32 %0, %1, %2" : "=v"(r) : "v"(lo), "v"(hi)); return r; }
;     __device__ __forceinline__ void epi(Acc& acc, const Unit& u, int wr, int wc, int fr, int fq) const {
;     ...
;         if (u.kind == 0) {
;             const int b16 = u.pm >> 4;
; #pragma unroll
;             for (int ai = 0; ai < 2; ++ai) {
;                 f32x4 gv[2][2];
; #pragma unroll
;                 for (int bj = 0; bj < 2; ++bj)
; #pragma unroll
;                     for (int n = 0; n < 2; ++n) gv[bj][n] = *(const f32x4*)(gate + (size_t)b16 * 6144 + u.pn * 256 + bj * 128 + wc * 32 + fq * 8 + n * 4);
; #pragma unroll
;                 for (int m = 0; m < 4; ++m) { const int row = u.pm * 256 + ai * 128 + rl0 + m * 16;
; #pragma unroll
;                     for (int bj = 0; bj < 2; ++bj) { const int col = u.pn * 256 + bj * 128 + wc * 32 + fq * 8;
;                         if constexpr (MODE == 0) {
;                             const float* bp = xp + (size_t)row * DM;
;                             const f32x4 r0 = *(const f32x4*)(bp + col) + gv[bj][0] * acc[ai][bj][m][0], r1 = *(const f32x4*)(bp + col + 4) + gv[bj][1] * acc[ai][bj][m][1];
;                             u32x4 w; w.x = cvt_pk_bf16(r0[0], r0[1]); w.y = cvt_pk_bf16(r0[2], r0[3]); w.z = cvt_pk_bf16(r1[0], r1[1]); w.w = cvt_pk_bf16(r1[2], r1[3]);
;                             *(u32x4*)(X1 + (size_t)row * DM + col) = w;
	v_pk_fma_f32 v[48:49], v[42:43], v[66:67], v[54:55]
	v_pk_fma_f32 v[42:43], v[40:41], v[64:65], v[52:53]
	v_pk_fma_f32 v[46:47], v[46:47], v[70:71], v[50:51]
	v_cvt_pk_bf16_f32 v40, v44, v45
	v_cvt_pk_bf16_f32 v42, v42, v43
	v_cvt_pk_bf16_f32 v43, v48, v49
	v_add_u32_e32 v48, 0xa0, v156
	v_cvt_pk_bf16_f32 v41, v46, v47
	global_store_dwordx4 v[56:57], v[40:43], off
	global_load_dwordx4 v[40:43], v[82:83], off offset:512 nt
	s_nop 0
	global_load_dwordx4 v[44:47], v[82:83], off offset:528 nt
	v_ashrrev_i32_e32 v49, 31, v48
	v_lshlrev_b64 v[50:51], 12, v[48:49]
	v_lshl_add_u64 v[50:51], s[12:13], 0, v[50:51]
	v_lshl_add_u64 v[50:51], v[50:51], 0, v[158:159]
	s_waitcnt vmcnt(1)
	v_pk_fma_f32 v[36:37], v[36:37], v[76:77], v[40:41]
	s_waitcnt vmcnt(0)
	v_pk_fma_f32 v[40:41], v[34:35], v[74:75], v[46:47]
	v_pk_fma_f32 v[34:35], v[32:33], v[72:73], v[44:45]
	v_pk_fma_f32 v[38:39], v[38:39], v[78:79], v[42:43]
	v_cvt_pk_bf16_f32 v32, v36, v37
	v_cvt_pk_bf16_f32 v34, v34, v35
	v_cvt_pk_bf16_f32 v35, v40, v41
	v_lshlrev_b64 v[40:41], 11, v[48:49]
	v_cvt_pk_bf16_f32 v33, v38, v39
	global_store_dwordx4 v[56:57], v[32:35], off offset:256
	global_load_dwordx4 v[32:35], v[50:51], off nt
	s_nop 0
	global_load_dwordx4 v[36:39], v[50:51], off offset:16 nt
	v_lshl_add_u64 v[40:41], s[4:5], 0, v[40:41]
	v_lshl_add_u64 v[40:41], v[40:41], 0, v[160:161]
	s_waitcnt vmcnt(1)
	v_pk_fma_f32 v[28:29], v[28:29], v[68:69], v[32:33]
	s_waitcnt vmcnt(0)
	v_pk_fma_f32 v[32:33], v[26:27], v[66:67], v[38:39]
	v_pk_fma_f32 v[26:27], v[24:25], v[64:65], v[36:37]
	v_pk_fma_f32 v[30:31], v[30:31], v[70:71], v[34:35]
	v_cvt_pk_bf16_f32 v24, v28, v29
	v_cvt_pk_bf16_f32 v26, v26, v27
	v_cvt_pk_bf16_f32 v27, v32, v33
	v_add_u32_e32 v32, 0xb0, v156
	v_cvt_pk_bf16_f32 v25, v30, v31
	global_store_dwordx4 v[40:41], v[24:27], off
	global_load_dwordx4 v[24:27], v[50:51], off offset:512 nt
	s_nop 0
	global_load_dwordx4 v[28:31], v[50:51], off offset:528 nt
	v_ashrrev_i32_e32 v33, 31, v32
	v_lshlrev_b64 v[34:35], 12, v[32:33]
	v_lshl_add_u64 v[34:35], s[12:13], 0, v[34:35]
	v_lshl_add_u64 v[34:35], v[34:35], 0, v[158:159]
	s_waitcnt vmcnt(1)
	v_pk_fma_f32 v[20:21], v[20:21], v[76:77], v[24:25]
	s_waitcnt vmcnt(0)
	v_pk_fma_f32 v[24:25], v[18:19], v[74:75], v[30:31]
	v_pk_fma_f32 v[18:19], v[16:17], v[72:73], v[28:29]
	v_pk_fma_f32 v[22:23], v[22:23], v[78:79], v[26:27]
	v_cvt_pk_bf16_f32 v16, v20, v21
	v_cvt_pk_bf16_f32 v18, v18, v19
	v_cvt_pk_bf16_f32 v19, v24, v25
	v_lshlrev_b64 v[24:25], 11, v[32:33]
	v_cvt_pk_bf16_f32 v17, v22, v23
	global_store_dwordx4 v[40:41], v[16:19], off offset:256
	global_load_dwordx4 v[16:19], v[34:35], off nt
	s_nop 0
	global_load_dwordx4 v[20:23], v[34:35], off offset:16 nt
	v_lshl_add_u64 v[24:25], s[4:5], 0, v[24:25]
	v_lshl_add_u64 v[24:25], v[24:25], 0, v[160:161]
	s_waitcnt vmcnt(1)
	v_pk_fma_f32 v[12:13], v[12:13], v[68:69], v[16:17]
	s_waitcnt vmcnt(0)
	v_pk_fma_f32 v[16:17], v[10:11], v[66:67], v[22:23]
	v_pk_fma_f32 v[10:11], v[8:9], v[64:65], v[20:21]
	v_pk_fma_f32 v[14:15], v[14:15], v[70:71], v[18:19]
	v_cvt_pk_bf16_f32 v8, v12, v13
	v_cvt_pk_bf16_f32 v10, v10, v11
	v_cvt_pk_bf16_f32 v11, v16, v17
	s_nop 0
	v_cvt_pk_bf16_f32 v9, v14, v15
	global_store_dwordx4 v[24:25], v[8:11], off
	global_load_dwordx4 v[8:11], v[34:35], off offset:512 nt
	s_nop 0
	global_load_dwordx4 v[12:15], v[34:35], off offset:528 nt
	s_waitcnt vmcnt(1)
	v_pk_fma_f32 v[4:5], v[4:5], v[76:77], v[8:9]
	s_waitcnt vmcnt(0)
	v_pk_fma_f32 v[8:9], v[2:3], v[74:75], v[14:15]
	v_pk_fma_f32 v[2:3], v[0:1], v[72:73], v[12:13]
	v_pk_fma_f32 v[6:7], v[6:7], v[78:79], v[10:11]
	v_cvt_pk_bf16_f32 v0, v4, v5
	v_cvt_pk_bf16_f32 v2, v2, v3
	v_cvt_pk_bf16_f32 v3, v8, v9
	s_nop 0
	v_cvt_pk_bf16_f32 v1, v6, v7
	global_store_dwordx4 v[24:25], v[0:3], off offset:256
	s_and_b64 vcc, exec, s[0:1]
	s_mov_b64 s[0:1], -1
	s_cbranch_vccnz .LBB0_1025

; __device__ __forceinline__ void row_load_bf16(const bf16_t* row, f32x4 (&v)[4], int lane) {
; #pragma unroll
;     for (int j = 0; j < 4; ++j) { const u32x2 w = *((const u32x2*)row + lane + 64 * j);
;         v[j] = (f32x4){__uint_as_float(w.x << 16), __uint_as_float(w.x & 0xffff0000u), __uint_as_float(w.y << 16), __uint_as_float(w.y & 0xffff0000u)}; }
; }
; __global__ void __launch_bounds__(512, 2) mega_fwd(Args a) {
;     ...
;         int row = bx * 8 + wid; f32x4 nv[4];
;         if (row < MP) row_load_bf16(X1B + (size_t)row * DM, nv, lane);
;         for (; row < MP; row += G * 8) {
;             f32x4 v[4];
; #pragma unroll
;             for (int j = 0; j < 4; ++j) v[j] = nv[j];
;             const int nr = row + G * 8;
;             if (nr < MP) row_load_bf16(X1B + (size_t)nr * DM, nv, lane);
;             const int b16 = row >> 12;
;             norm_apply(v, norm2_g, MOD + (size_t)b16 * 6144 + 4096, MOD + (size_t)b16 * 6144 + 3072, Hb + (size_t)row * DM, lane);
.LBB0_1100:
	s_or_b64 exec, exec, s[0:1]
	s_waitcnt lgkmcnt(0)
	v_mov_b32_e32 v0, v211
	s_barrier
	s_nop 0
	v_readfirstlane_b32 s0, v0
	s_ashr_i32 s7, s0, 6
	v_readlane_b32 s0, v238, 46
	v_and_b32_e32 v4, 63, v0
	s_add_i32 s26, s7, s0
	s_cmpk_gt_i32 s26, 0x7fff
	v_lshlrev_b32_e32 v10, 3, v4
	v_lshlrev_b32_e32 v0, 4, v4
	v_or_b32_e32 v6, 64, v4
	s_cbranch_scc1 .LBB0_1105
	v_readlane_b32 s46, v238, 30
	v_readlane_b32 s47, v238, 31
	v_lshlrev_b32_e32 v1, 5, v4
	v_xor_b32_e32 v2, 1, v4
	v_lshlrev_b32_e32 v2, 2, v2
	v_xor_b32_e32 v3, 2, v4
	v_lshlrev_b32_e32 v3, 2, v3
	v_xor_b32_e32 v5, 4, v4
	v_lshlrev_b32_e32 v5, 2, v5
	v_xor_b32_e32 v7, 8, v4
	v_lshlrev_b32_e32 v7, 2, v7
	v_xor_b32_e32 v8, 16, v4
	v_lshlrev_b32_e32 v8, 2, v8
	v_xor_b32_e32 v9, 32, v4
	v_lshlrev_b32_e32 v9, 2, v9
	global_load_dwordx4 v[16:19], v1, s[46:47]
	global_load_dwordx4 v[20:23], v1, s[46:47] offset:16
	global_load_dwordx4 v[24:27], v1, s[46:47] offset:2048
	global_load_dwordx4 v[28:31], v1, s[46:47] offset:2064
	s_lshr_b32 s23, s26, 12
	s_mul_i32 s23, s23, 0x6000
	s_add_u32 s8, s30, s23
	s_addc_u32 s9, s31, 0
	s_add_u32 s10, s8, 0x4000
	s_addc_u32 s11, s9, 0
	s_add_u32 s8, s8, 0x3000
	s_addc_u32 s9, s9, 0
	global_load_dwordx4 v[32:35], v1, s[10:11]
	global_load_dwordx4 v[36:39], v1, s[10:11] offset:16
	global_load_dwordx4 v[40:43], v1, s[10:11] offset:2048
	global_load_dwordx4 v[44:47], v1, s[10:11] offset:2064
	global_load_dwordx4 v[48:51], v1, s[8:9]
	global_load_dwordx4 v[52:55], v1, s[8:9] offset:16
	global_load_dwordx4 v[56:59], v1, s[8:9] offset:2048
	global_load_dwordx4 v[60:63], v1, s[8:9] offset:2064
	s_lshl_b32 s0, s26, 11
	s_add_u32 s0, s4, s0
	s_addc_u32 s1, s5, 0
	global_load_dwordx4 v[96:99], v0, s[0:1] nt
	global_load_dwordx4 v[100:103], v0, s[0:1] offset:1024 nt
	s_add_i32 s22, s26, s88
	s_min_i32 s22, s22, 0x7fff
	s_lshl_b32 s0, s22, 11
	s_add_u32 s0, s4, s0
	s_addc_u32 s1, s5, 0
	global_load_dwordx4 v[104:107], v0, s[0:1] nt
	global_load_dwordx4 v[108:111], v0, s[0:1] offset:1024 nt
	s_add_i32 s22, s26, s88
	s_add_i32 s22, s22, s88
	s_min_i32 s22, s22, 0x7fff
	s_lshr_b32 s23, s22, 12
	s_mul_i32 s23, s23, 0x6000
	s_add_u32 s8, s30, s23
	s_addc_u32 s9, s31, 0
	s_add_u32 s10, s8, 0x4000
	s_addc_u32 s11, s9, 0
	s_add_u32 s8, s8, 0x3000
	s_addc_u32 s9, s9, 0
	global_load_dwordx4 v[64:67], v1, s[10:11]
	global_load_dwordx4 v[68:71], v1, s[10:11] offset:16
	global_load_dwordx4 v[72:75], v1, s[10:11] offset:2048
	global_load_dwordx4 v[76:79], v1, s[10:11] offset:2064
	global_load_dwordx4 v[80:83], v1, s[8:9]
	global_load_dwordx4 v[84:87], v1, s[8:9] offset:16
	global_load_dwordx4 v[88:91], v1, s[8:9] offset:2048
	global_load_dwordx4 v[92:95], v1, s[8:9] offset:2064
	s_waitcnt vmcnt(10)
	s_branch .Lp6_e0_go

; __device__ __forceinline__ unsigned cvt_pk_bf16(float lo, float hi) { unsigned r; asm("v_cvt_pk_bf16_f32 %0, %1, %2" : "=v"(r) : "v"(lo), "v"(hi)); return r; }
; __device__ __forceinline__ void norm_apply(const f32x4 (&v)[4], const float* g, const float* sc, const float* sh, bf16_t* orow, int lane) {
;     float s = 0.f;
; #pragma unroll
;     for (int j = 0; j < 4; ++j) s += (v[j][0] * v[j][0] + v[j][1] * v[j][1]) + (v[j][2] * v[j][2] + v[j][3] * v[j][3]);
;     const float rstd = rsqrtf(wave_sum(s) * (1.f / 1024.f) + EPS);
; #pragma unroll
;     for (int j = 0; j < 4; ++j) { const int c4 = lane + 64 * j;
;         const f32x4 gg = *((const f32x4*)g + c4), cc = *((const f32x4*)sc + c4), hh = *((const f32x4*)sh + c4);
;         const f32x4 h = v[j] * rstd * gg * (cc + 1.f) + hh;
;         u32x2 w; w.x = cvt_pk_bf16(h[0], h[1]); w.y = cvt_pk_bf16(h[2], h[3]);
;         *((u32x2*)orow + c4) = w; }
; }
; __device__ __forceinline__ void row_load_bf16(const bf16_t* row, f32x4 (&v)[4], int lane) {
; #pragma unroll
;     for (int j = 0; j < 4; ++j) { const u32x2 w = *((const u32x2*)row + lane + 64 * j);
;         v[j] = (f32x4){__uint_as_float(w.x << 16), __uint_as_float(w.x & 0xffff0000u), __uint_as_float(w.y << 16), __uint_as_float(w.y & 0xffff0000u)}; }
; }
.Lp6_e0_go:
	v_lshlrev_b32_e32 v120, 16, v96
	v_and_b32_e32 v121, 0xffff0000, v96
	v_lshlrev_b32_e32 v122, 16, v97
	v_and_b32_e32 v123, 0xffff0000, v97
	v_lshlrev_b32_e32 v124, 16, v98
	v_and_b32_e32 v125, 0xffff0000, v98
	v_lshlrev_b32_e32 v126, 16, v99
	v_and_b32_e32 v127, 0xffff0000, v99
	v_lshlrev_b32_e32 v128, 16, v100
	v_and_b32_e32 v129, 0xffff0000, v100
	v_lshlrev_b32_e32 v130, 16, v101
	v_and_b32_e32 v131, 0xffff0000, v101
	v_lshlrev_b32_e32 v132, 16, v102
	v_and_b32_e32 v133, 0xffff0000, v102
	v_lshlrev_b32_e32 v134, 16, v103
	v_and_b32_e32 v135, 0xffff0000, v103
	s_add_i32 s22, s26, s88
	s_add_i32 s22, s22, s88
	s_min_i32 s22, s22, 0x7fff
	s_lshl_b32 s0, s22, 11
	s_add_u32 s0, s4, s0
	s_addc_u32 s1, s5, 0
	global_load_dwordx4 v[96:99], v0, s[0:1] nt
	global_load_dwordx4 v[100:103], v0, s[0:1] offset:1024 nt
	v_mul_f32_e32 v11, v120, v120
	v_mul_f32_e32 v12, v121, v121
	v_fmac_f32_e32 v11, v122, v122
	v_fmac_f32_e32 v12, v123, v123
	v_fmac_f32_e32 v11, v124, v124
	v_fmac_f32_e32 v12, v125, v125
	v_fmac_f32_e32 v11, v126, v126
	v_fmac_f32_e32 v12, v127, v127
	v_fmac_f32_e32 v11, v128, v128
	v_fmac_f32_e32 v12, v129, v129
	v_fmac_f32_e32 v11, v130, v130
	v_fmac_f32_e32 v12, v131, v131
	v_fmac_f32_e32 v11, v132, v132
	v_fmac_f32_e32 v12, v133, v133
	v_fmac_f32_e32 v11, v134, v134
	v_fmac_f32_e32 v12, v135, v135
	v_add_f32_e32 v11, v11, v12
	ds_bpermute_b32 v12, v2, v11
	s_waitcnt lgkmcnt(0)
	v_add_f32_e32 v11, v11, v12
	ds_bpermute_b32 v12, v3, v11
	s_waitcnt lgkmcnt(0)
	v_add_f32_e32 v11, v11, v12
	ds_bpermute_b32 v12, v5, v11
	s_waitcnt lgkmcnt(0)
	v_add_f32_e32 v11, v11, v12
	ds_bpermute_b32 v12, v7, v11
	s_waitcnt lgkmcnt(0)
	v_add_f32_e32 v11, v11, v12
	ds_bpermute_b32 v12, v8, v11
	s_waitcnt lgkmcnt(0)
	v_add_f32_e32 v11, v11, v12
	ds_bpermute_b32 v12, v9, v11
	s_waitcnt lgkmcnt(0)
	v_add_f32_e32 v11, v11, v12
	v_mov_b32_e32 v12, 0x358637bd
	v_fmac_f32_e32 v12, 0x3a800000, v11
	v_rsq_f32_e32 v13, v12
	s_nop 0
	s_lshl_b32 s12, s26, 11
	s_add_u32 s12, s30, s12
	s_addc_u32 s13, s31, 0
	s_add_u32 s12, s12, 0x1d00000
	s_addc_u32 s13, s13, 0
	v_mul_f32_e32 v120, v13, v120
	v_mul_f32_e32 v121, v13, v121
	v_mul_f32_e32 v122, v13, v122
	v_mul_f32_e32 v123, v13, v123
	v_mul_f32_e32 v124, v13, v124
	v_mul_f32_e32 v125, v13, v125
	v_mul_f32_e32 v126, v13, v126
	v_mul_f32_e32 v127, v13, v127
	v_mul_f32_e32 v128, v13, v128
	v_mul_f32_e32 v129, v13, v129
	v_mul_f32_e32 v130, v13, v130
	v_mul_f32_e32 v131, v13, v131
	v_mul_f32_e32 v132, v13, v132
	v_mul_f32_e32 v133, v13, v133
	v_mul_f32_e32 v134, v13, v134
	v_mul_f32_e32 v135, v13, v135
	v_mul_f32_e32 v120, v16, v120
	v_mul_f32_e32 v121, v17, v121
	v_mul_f32_e32 v122, v18, v122
	v_mul_f32_e32 v123, v19, v123
	v_mul_f32_e32 v124, v20, v124
	v_mul_f32_e32 v125, v21, v125
	v_mul_f32_e32 v126, v22, v126
	v_mul_f32_e32 v127, v23, v127
	v_mul_f32_e32 v128, v24, v128
	v_mul_f32_e32 v129, v25, v129
	v_mul_f32_e32 v130, v26, v130
	v_mul_f32_e32 v131, v27, v131
	v_mul_f32_e32 v132, v28, v132
	v_mul_f32_e32 v133, v29, v133
	v_mul_f32_e32 v134, v30, v134
	v_mul_f32_e32 v135, v31, v135
	v_add_f32_e32 v32, 1.0, v32
	v_add_f32_e32 v33, 1.0, v33
	v_add_f32_e32 v34, 1.0, v34
	v_add_f32_e32 v35, 1.0, v35
	v_add_f32_e32 v36, 1.0, v36
	v_add_f32_e32 v37, 1.0, v37
	v_add_f32_e32 v38, 1.0, v38
	v_add_f32_e32 v39, 1.0, v39
	v_add_f32_e32 v40, 1.0, v40
	v_add_f32_e32 v41, 1.0, v41
	v_add_f32_e32 v42, 1.0, v42
	v_add_f32_e32 v43, 1.0, v43
	v_add_f32_e32 v44, 1.0, v44
	v_add_f32_e32 v45, 1.0, v45
	v_add_f32_e32 v46, 1.0, v46
	v_add_f32_e32 v47, 1.0, v47
	v_fma_f32 v120, v32, v120, v48
	v_fma_f32 v121, v33, v121, v49
	v_fma_f32 v122, v34, v122, v50
	v_fma_f32 v123, v35, v123, v51
	v_fma_f32 v124, v36, v124, v52
	v_fma_f32 v125, v37, v125, v53
	v_fma_f32 v126, v38, v126, v54
	v_fma_f32 v127, v39, v127, v55
	v_fma_f32 v128, v40, v128, v56
	v_fma_f32 v129, v41, v129, v57
	v_fma_f32 v130, v42, v130, v58
	v_fma_f32 v131, v43, v131, v59
	v_fma_f32 v132, v44, v132, v60
	v_fma_f32 v133, v45, v133, v61
	v_fma_f32 v134, v46, v134, v62
	v_fma_f32 v135, v47, v135, v63
	v_cvt_pk_bf16_f32 v120, v120, v121
	v_cvt_pk_bf16_f32 v121, v122, v123
	v_cvt_pk_bf16_f32 v122, v124, v125
	v_cvt_pk_bf16_f32 v123, v126, v127
	v_cvt_pk_bf16_f32 v124, v128, v129
	v_cvt_pk_bf16_f32 v125, v130, v131
	v_cvt_pk_bf16_f32 v126, v132, v133
	v_cvt_pk_bf16_f32 v127, v134, v135
	global_store_dwordx4 v0, v[120:123], s[12:13]
	global_store_dwordx4 v0, v[124:127], s[12:13] offset:1024
	s_add_i32 s26, s26, s88
	s_cmpk_gt_i32 s26, 0x7fff
	s_cbranch_scc1 .Lp6_done

; __device__ __forceinline__ unsigned cvt_pk_bf16(float lo, float hi) { unsigned r; asm("v_cvt_pk_bf16_f32 %0, %1, %2" : "=v"(r) : "v"(lo), "v"(hi)); return r; }
; __device__ __forceinline__ void norm_apply(const f32x4 (&v)[4], const float* g, const float* sc, const float* sh, bf16_t* orow, int lane) {
;     float s = 0.f;
; #pragma unroll
;     for (int j = 0; j < 4; ++j) s += (v[j][0] * v[j][0] + v[j][1] * v[j][1]) + (v[j][2] * v[j][2] + v[j][3] * v[j][3]);
;     const float rstd = rsqrtf(wave_sum(s) * (1.f / 1024.f) + EPS);
; #pragma unroll
;     for (int j = 0; j < 4; ++j) { const int c4 = lane + 64 * j;
;         const f32x4 gg = *((const f32x4*)g + c4), cc = *((const f32x4*)sc + c4), hh = *((const f32x4*)sh + c4);
;         const f32x4 h = v[j] * rstd * gg * (cc + 1.f) + hh;
;         u32x2 w; w.x = cvt_pk_bf16(h[0], h[1]); w.y = cvt_pk_bf16(h[2], h[3]);
;         *((u32x2*)orow + c4) = w; }
; }
; __device__ __forceinline__ void row_load_bf16(const bf16_t* row, f32x4 (&v)[4], int lane) {
; #pragma unroll
;     for (int j = 0; j < 4; ++j) { const u32x2 w = *((const u32x2*)row + lane + 64 * j);
;         v[j] = (f32x4){__uint_as_float(w.x << 16), __uint_as_float(w.x & 0xffff0000u), __uint_as_float(w.y << 16), __uint_as_float(w.y & 0xffff0000u)}; }
; }
.Lp6_o0_go:
	v_lshlrev_b32_e32 v120, 16, v104
	v_and_b32_e32 v121, 0xffff0000, v104
	v_lshlrev_b32_e32 v122, 16, v105
	v_and_b32_e32 v123, 0xffff0000, v105
	v_lshlrev_b32_e32 v124, 16, v106
	v_and_b32_e32 v125, 0xffff0000, v106
	v_lshlrev_b32_e32 v126, 16, v107
	v_and_b32_e32 v127, 0xffff0000, v107
	v_lshlrev_b32_e32 v128, 16, v108
	v_and_b32_e32 v129, 0xffff0000, v108
	v_lshlrev_b32_e32 v130, 16, v109
	v_and_b32_e32 v131, 0xffff0000, v109
	v_lshlrev_b32_e32 v132, 16, v110
	v_and_b32_e32 v133, 0xffff0000, v110
	v_lshlrev_b32_e32 v134, 16, v111
	v_and_b32_e32 v135, 0xffff0000, v111
	s_add_i32 s22, s26, s88
	s_add_i32 s22, s22, s88
	s_min_i32 s22, s22, 0x7fff
	s_lshl_b32 s0, s22, 11
	s_add_u32 s0, s4, s0
	s_addc_u32 s1, s5, 0
	global_load_dwordx4 v[104:107], v0, s[0:1] nt
	global_load_dwordx4 v[108:111], v0, s[0:1] offset:1024 nt
	v_mul_f32_e32 v11, v120, v120
	v_mul_f32_e32 v12, v121, v121
	v_fmac_f32_e32 v11, v122, v122
	v_fmac_f32_e32 v12, v123, v123
	v_fmac_f32_e32 v11, v124, v124
	v_fmac_f32_e32 v12, v125, v125
	v_fmac_f32_e32 v11, v126, v126
	v_fmac_f32_e32 v12, v127, v127
	v_fmac_f32_e32 v11, v128, v128
	v_fmac_f32_e32 v12, v129, v129
	v_fmac_f32_e32 v11, v130, v130
	v_fmac_f32_e32 v12, v131, v131
	v_fmac_f32_e32 v11, v132, v132
	v_fmac_f32_e32 v12, v133, v133
	v_fmac_f32_e32 v11, v134, v134
	v_fmac_f32_e32 v12, v135, v135
	v_add_f32_e32 v11, v11, v12
	ds_bpermute_b32 v12, v2, v11
	s_waitcnt lgkmcnt(0)
	v_add_f32_e32 v11, v11, v12
	ds_bpermute_b32 v12, v3, v11
	s_waitcnt lgkmcnt(0)
	v_add_f32_e32 v11, v11, v12
	ds_bpermute_b32 v12, v5, v11
	s_waitcnt lgkmcnt(0)
	v_add_f32_e32 v11, v11, v12
	ds_bpermute_b32 v12, v7, v11
	s_waitcnt lgkmcnt(0)
	v_add_f32_e32 v11, v11, v12
	ds_bpermute_b32 v12, v8, v11
	s_waitcnt lgkmcnt(0)
	v_add_f32_e32 v11, v11, v12
	ds_bpermute_b32 v12, v9, v11
	s_waitcnt lgkmcnt(0)
	v_add_f32_e32 v11, v11, v12
	v_mov_b32_e32 v12, 0x358637bd
	v_fmac_f32_e32 v12, 0x3a800000, v11
	v_rsq_f32_e32 v13, v12
	s_nop 0
	s_lshl_b32 s12, s26, 11
	s_add_u32 s12, s30, s12
	s_addc_u32 s13, s31, 0
	s_add_u32 s12, s12, 0x1d00000
	s_addc_u32 s13, s13, 0
	v_mul_f32_e32 v120, v13, v120
	v_mul_f32_e32 v121, v13, v121
	v_mul_f32_e32 v122, v13, v122
	v_mul_f32_e32 v123, v13, v123
	v_mul_f32_e32 v124, v13, v124
	v_mul_f32_e32 v125, v13, v125
	v_mul_f32_e32 v126, v13, v126
	v_mul_f32_e32 v127, v13, v127
	v_mul_f32_e32 v128, v13, v128
	v_mul_f32_e32 v129, v13, v129
	v_mul_f32_e32 v130, v13, v130
	v_mul_f32_e32 v131, v13, v131
	v_mul_f32_e32 v132, v13, v132
	v_mul_f32_e32 v133, v13, v133
	v_mul_f32_e32 v134, v13, v134
	v_mul_f32_e32 v135, v13, v135
	v_mul_f32_e32 v120, v16, v120
	v_mul_f32_e32 v121, v17, v121
	v_mul_f32_e32 v122, v18, v122
	v_mul_f32_e32 v123, v19, v123
	v_mul_f32_e32 v124, v20, v124
	v_mul_f32_e32 v125, v21, v125
	v_mul_f32_e32 v126, v22, v126
	v_mul_f32_e32 v127, v23, v127
	v_mul_f32_e32 v128, v24, v128
	v_mul_f32_e32 v129, v25, v129
	v_mul_f32_e32 v130, v26, v130
	v_mul_f32_e32 v131, v27, v131
	v_mul_f32_e32 v132, v28, v132
	v_mul_f32_e32 v133, v29, v133
	v_mul_f32_e32 v134, v30, v134
	v_mul_f32_e32 v135, v31, v135
	v_fma_f32 v120, v32, v120, v48
	v_fma_f32 v121, v33, v121, v49
	v_fma_f32 v122, v34, v122, v50
	v_fma_f32 v123, v35, v123, v51
	v_fma_f32 v124, v36, v124, v52
	v_fma_f32 v125, v37, v125, v53
	v_fma_f32 v126, v38, v126, v54
	v_fma_f32 v127, v39, v127, v55
	v_fma_f32 v128, v40, v128, v56
	v_fma_f32 v129, v41, v129, v57
	v_fma_f32 v130, v42, v130, v58
	v_fma_f32 v131, v43, v131, v59
	v_fma_f32 v132, v44, v132, v60
	v_fma_f32 v133, v45, v133, v61
	v_fma_f32 v134, v46, v134, v62
	v_fma_f32 v135, v47, v135, v63
	v_cvt_pk_bf16_f32 v120, v120, v121
	v_cvt_pk_bf16_f32 v121, v122, v123
	v_cvt_pk_bf16_f32 v122, v124, v125
	v_cvt_pk_bf16_f32 v123, v126, v127
	v_cvt_pk_bf16_f32 v124, v128, v129
	v_cvt_pk_bf16_f32 v125, v130, v131
	v_cvt_pk_bf16_f32 v126, v132, v133
	v_cvt_pk_bf16_f32 v127, v134, v135
	global_store_dwordx4 v0, v[120:123], s[12:13]
	global_store_dwordx4 v0, v[124:127], s[12:13] offset:1024
	s_add_i32 s26, s26, s88
	s_cmpk_gt_i32 s26, 0x7fff
	s_cbranch_scc1 .Lp6_done

; __device__ __forceinline__ unsigned cvt_pk_bf16(float lo, float hi) { unsigned r; asm("v_cvt_pk_bf16_f32 %0, %1, %2" : "=v"(r) : "v"(lo), "v"(hi)); return r; }
; __device__ __forceinline__ void norm_apply(const f32x4 (&v)[4], const float* g, const float* sc, const float* sh, bf16_t* orow, int lane) {
;     float s = 0.f;
; #pragma unroll
;     for (int j = 0; j < 4; ++j) s += (v[j][0] * v[j][0] + v[j][1] * v[j][1]) + (v[j][2] * v[j][2] + v[j][3] * v[j][3]);
;     const float rstd = rsqrtf(wave_sum(s) * (1.f / 1024.f) + EPS);
; #pragma unroll
;     for (int j = 0; j < 4; ++j) { const int c4 = lane + 64 * j;
;         const f32x4 gg = *((const f32x4*)g + c4), cc = *((const f32x4*)sc + c4), hh = *((const f32x4*)sh + c4);
;         const f32x4 h = v[j] * rstd * gg * (cc + 1.f) + hh;
;         u32x2 w; w.x = cvt_pk_bf16(h[0], h[1]); w.y = cvt_pk_bf16(h[2], h[3]);
;         *((u32x2*)orow + c4) = w; }
; }
; __device__ __forceinline__ void row_load_bf16(const bf16_t* row, f32x4 (&v)[4], int lane) {
; #pragma unroll
;     for (int j = 0; j < 4; ++j) { const u32x2 w = *((const u32x2*)row + lane + 64 * j);
;         v[j] = (f32x4){__uint_as_float(w.x << 16), __uint_as_float(w.x & 0xffff0000u), __uint_as_float(w.y << 16), __uint_as_float(w.y & 0xffff0000u)}; }
; }
.Lp6_e1_go:
	v_lshlrev_b32_e32 v120, 16, v96
	v_and_b32_e32 v121, 0xffff0000, v96
	v_lshlrev_b32_e32 v122, 16, v97
	v_and_b32_e32 v123, 0xffff0000, v97
	v_lshlrev_b32_e32 v124, 16, v98
	v_and_b32_e32 v125, 0xffff0000, v98
	v_lshlrev_b32_e32 v126, 16, v99
	v_and_b32_e32 v127, 0xffff0000, v99
	v_lshlrev_b32_e32 v128, 16, v100
	v_and_b32_e32 v129, 0xffff0000, v100
	v_lshlrev_b32_e32 v130, 16, v101
	v_and_b32_e32 v131, 0xffff0000, v101
	v_lshlrev_b32_e32 v132, 16, v102
	v_and_b32_e32 v133, 0xffff0000, v102
	v_lshlrev_b32_e32 v134, 16, v103
	v_and_b32_e32 v135, 0xffff0000, v103
	s_add_i32 s22, s26, s88
	s_add_i32 s22, s22, s88
	s_min_i32 s22, s22, 0x7fff
	s_lshl_b32 s0, s22, 11
	s_add_u32 s0, s4, s0
	s_addc_u32 s1, s5, 0
	global_load_dwordx4 v[96:99], v0, s[0:1] nt
	global_load_dwordx4 v[100:103], v0, s[0:1] offset:1024 nt
	v_mul_f32_e32 v11, v120, v120
	v_mul_f32_e32 v12, v121, v121
	v_fmac_f32_e32 v11, v122, v122
	v_fmac_f32_e32 v12, v123, v123
	v_fmac_f32_e32 v11, v124, v124
	v_fmac_f32_e32 v12, v125, v125
	v_fmac_f32_e32 v11, v126, v126
	v_fmac_f32_e32 v12, v127, v127
	v_fmac_f32_e32 v11, v128, v128
	v_fmac_f32_e32 v12, v129, v129
	v_fmac_f32_e32 v11, v130, v130
	v_fmac_f32_e32 v12, v131, v131
	v_fmac_f32_e32 v11, v132, v132
	v_fmac_f32_e32 v12, v133, v133
	v_fmac_f32_e32 v11, v134, v134
	v_fmac_f32_e32 v12, v135, v135
	v_add_f32_e32 v11, v11, v12
	ds_bpermute_b32 v12, v2, v11
	s_waitcnt lgkmcnt(0)
	v_add_f32_e32 v11, v11, v12
	ds_bpermute_b32 v12, v3, v11
	s_waitcnt lgkmcnt(0)
	v_add_f32_e32 v11, v11, v12
	ds_bpermute_b32 v12, v5, v11
	s_waitcnt lgkmcnt(0)
	v_add_f32_e32 v11, v11, v12
	ds_bpermute_b32 v12, v7, v11
	s_waitcnt lgkmcnt(0)
	v_add_f32_e32 v11, v11, v12
	ds_bpermute_b32 v12, v8, v11
	s_waitcnt lgkmcnt(0)
	v_add_f32_e32 v11, v11, v12
	ds_bpermute_b32 v12, v9, v11
	s_waitcnt lgkmcnt(0)
	v_add_f32_e32 v11, v11, v12
	v_mov_b32_e32 v12, 0x358637bd
	v_fmac_f32_e32 v12, 0x3a800000, v11
	v_rsq_f32_e32 v13, v12
	s_nop 0
	s_lshl_b32 s12, s26, 11
	s_add_u32 s12, s30, s12
	s_addc_u32 s13, s31, 0
	s_add_u32 s12, s12, 0x1d00000
	s_addc_u32 s13, s13, 0
	v_mul_f32_e32 v120, v13, v120
	v_mul_f32_e32 v121, v13, v121
	v_mul_f32_e32 v122, v13, v122
	v_mul_f32_e32 v123, v13, v123
	v_mul_f32_e32 v124, v13, v124
	v_mul_f32_e32 v125, v13, v125
	v_mul_f32_e32 v126, v13, v126
	v_mul_f32_e32 v127, v13, v127
	v_mul_f32_e32 v128, v13, v128
	v_mul_f32_e32 v129, v13, v129
	v_mul_f32_e32 v130, v13, v130
	v_mul_f32_e32 v131, v13, v131
	v_mul_f32_e32 v132, v13, v132
	v_mul_f32_e32 v133, v13, v133
	v_mul_f32_e32 v134, v13, v134
	v_mul_f32_e32 v135, v13, v135
	v_mul_f32_e32 v120, v16, v120
	v_mul_f32_e32 v121, v17, v121
	v_mul_f32_e32 v122, v18, v122
	v_mul_f32_e32 v123, v19, v123
	v_mul_f32_e32 v124, v20, v124
	v_mul_f32_e32 v125, v21, v125
	v_mul_f32_e32 v126, v22, v126
	v_mul_f32_e32 v127, v23, v127
	v_mul_f32_e32 v128, v24, v128
	v_mul_f32_e32 v129, v25, v129
	v_mul_f32_e32 v130, v26, v130
	v_mul_f32_e32 v131, v27, v131
	v_mul_f32_e32 v132, v28, v132
	v_mul_f32_e32 v133, v29, v133
	v_mul_f32_e32 v134, v30, v134
	v_mul_f32_e32 v135, v31, v135
	v_add_f32_e32 v64, 1.0, v64
	v_add_f32_e32 v65, 1.0, v65
	v_add_f32_e32 v66, 1.0, v66
	v_add_f32_e32 v67, 1.0, v67
	v_add_f32_e32 v68, 1.0, v68
	v_add_f32_e32 v69, 1.0, v69
	v_add_f32_e32 v70, 1.0, v70
	v_add_f32_e32 v71, 1.0, v71
	v_add_f32_e32 v72, 1.0, v72
	v_add_f32_e32 v73, 1.0, v73
	v_add_f32_e32 v74, 1.0, v74
	v_add_f32_e32 v75, 1.0, v75
	v_add_f32_e32 v76, 1.0, v76
	v_add_f32_e32 v77, 1.0, v77
	v_add_f32_e32 v78, 1.0, v78
	v_add_f32_e32 v79, 1.0, v79
	v_fma_f32 v120, v64, v120, v80
	v_fma_f32 v121, v65, v121, v81
	v_fma_f32 v122, v66, v122, v82
	v_fma_f32 v123, v67, v123, v83
	v_fma_f32 v124, v68, v124, v84
	v_fma_f32 v125, v69, v125, v85
	v_fma_f32 v126, v70, v126, v86
	v_fma_f32 v127, v71, v127, v87
	v_fma_f32 v128, v72, v128, v88
	v_fma_f32 v129, v73, v129, v89
	v_fma_f32 v130, v74, v130, v90
	v_fma_f32 v131, v75, v131, v91
	v_fma_f32 v132, v76, v132, v92
	v_fma_f32 v133, v77, v133, v93
	v_fma_f32 v134, v78, v134, v94
	v_fma_f32 v135, v79, v135, v95
	v_cvt_pk_bf16_f32 v120, v120, v121
	v_cvt_pk_bf16_f32 v121, v122, v123
	v_cvt_pk_bf16_f32 v122, v124, v125
	v_cvt_pk_bf16_f32 v123, v126, v127
	v_cvt_pk_bf16_f32 v124, v128, v129
	v_cvt_pk_bf16_f32 v125, v130, v131
	v_cvt_pk_bf16_f32 v126, v132, v133
	v_cvt_pk_bf16_f32 v127, v134, v135
	global_store_dwordx4 v0, v[120:123], s[12:13]
	global_store_dwordx4 v0, v[124:127], s[12:13] offset:1024
	s_add_i32 s26, s26, s88
	s_cmpk_gt_i32 s26, 0x7fff
	s_cbranch_scc1 .Lp6_done

; __device__ __forceinline__ unsigned cvt_pk_bf16(float lo, float hi) { unsigned r; asm("v_cvt_pk_bf16_f32 %0, %1, %2" : "=v"(r) : "v"(lo), "v"(hi)); return r; }
; __device__ __forceinline__ void norm_apply(const f32x4 (&v)[4], const float* g, const float* sc, const float* sh, bf16_t* orow, int lane) {
;     float s = 0.f;
; #pragma unroll
;     for (int j = 0; j < 4; ++j) s += (v[j][0] * v[j][0] + v[j][1] * v[j][1]) + (v[j][2] * v[j][2] + v[j][3] * v[j][3]);
;     const float rstd = rsqrtf(wave_sum(s) * (1.f / 1024.f) + EPS);
; #pragma unroll
;     for (int j = 0; j < 4; ++j) { const int c4 = lane + 64 * j;
;         const f32x4 gg = *((const f32x4*)g + c4), cc = *((const f32x4*)sc + c4), hh = *((const f32x4*)sh + c4);
;         const f32x4 h = v[j] * rstd * gg * (cc + 1.f) + hh;
;         u32x2 w; w.x = cvt_pk_bf16(h[0], h[1]); w.y = cvt_pk_bf16(h[2], h[3]);
;         *((u32x2*)orow + c4) = w; }
; }
; __device__ __forceinline__ void row_load_bf16(const bf16_t* row, f32x4 (&v)[4], int lane) {
; #pragma unroll
;     for (int j = 0; j < 4; ++j) { const u32x2 w = *((const u32x2*)row + lane + 64 * j);
;         v[j] = (f32x4){__uint_as_float(w.x << 16), __uint_as_float(w.x & 0xffff0000u), __uint_as_float(w.y << 16), __uint_as_float(w.y & 0xffff0000u)}; }
; }
.Lp6_o1_go:
	v_lshlrev_b32_e32 v120, 16, v104
	v_and_b32_e32 v121, 0xffff0000, v104
	v_lshlrev_b32_e32 v122, 16, v105
	v_and_b32_e32 v123, 0xffff0000, v105
	v_lshlrev_b32_e32 v124, 16, v106
	v_and_b32_e32 v125, 0xffff0000, v106
	v_lshlrev_b32_e32 v126, 16, v107
	v_and_b32_e32 v127, 0xffff0000, v107
	v_lshlrev_b32_e32 v128, 16, v108
	v_and_b32_e32 v129, 0xffff0000, v108
	v_lshlrev_b32_e32 v130, 16, v109
	v_and_b32_e32 v131, 0xffff0000, v109
	v_lshlrev_b32_e32 v132, 16, v110
	v_and_b32_e32 v133, 0xffff0000, v110
	v_lshlrev_b32_e32 v134, 16, v111
	v_and_b32_e32 v135, 0xffff0000, v111
	s_add_i32 s22, s26, s88
	s_add_i32 s22, s22, s88
	s_min_i32 s22, s22, 0x7fff
	s_lshl_b32 s0, s22, 11
	s_add_u32 s0, s4, s0
	s_addc_u32 s1, s5, 0
	global_load_dwordx4 v[104:107], v0, s[0:1] nt
	global_load_dwordx4 v[108:111], v0, s[0:1] offset:1024 nt
	v_mul_f32_e32 v11, v120, v120
	v_mul_f32_e32 v12, v121, v121
	v_fmac_f32_e32 v11, v122, v122
	v_fmac_f32_e32 v12, v123, v123
	v_fmac_f32_e32 v11, v124, v124
	v_fmac_f32_e32 v12, v125, v125
	v_fmac_f32_e32 v11, v126, v126
	v_fmac_f32_e32 v12, v127, v127
	v_fmac_f32_e32 v11, v128, v128
	v_fmac_f32_e32 v12, v129, v129
	v_fmac_f32_e32 v11, v130, v130
	v_fmac_f32_e32 v12, v131, v131
	v_fmac_f32_e32 v11, v132, v132
	v_fmac_f32_e32 v12, v133, v133
	v_fmac_f32_e32 v11, v134, v134
	v_fmac_f32_e32 v12, v135, v135
	v_add_f32_e32 v11, v11, v12
	ds_bpermute_b32 v12, v2, v11
	s_waitcnt lgkmcnt(0)
	v_add_f32_e32 v11, v11, v12
	ds_bpermute_b32 v12, v3, v11
	s_waitcnt lgkmcnt(0)
	v_add_f32_e32 v11, v11, v12
	ds_bpermute_b32 v12, v5, v11
	s_waitcnt lgkmcnt(0)
	v_add_f32_e32 v11, v11, v12
	ds_bpermute_b32 v12, v7, v11
	s_waitcnt lgkmcnt(0)
	v_add_f32_e32 v11, v11, v12
	ds_bpermute_b32 v12, v8, v11
	s_waitcnt lgkmcnt(0)
	v_add_f32_e32 v11, v11, v12
	ds_bpermute_b32 v12, v9, v11
	s_waitcnt lgkmcnt(0)
	v_add_f32_e32 v11, v11, v12
	v_mov_b32_e32 v12, 0x358637bd
	v_fmac_f32_e32 v12, 0x3a800000, v11
	v_rsq_f32_e32 v13, v12
	s_nop 0
	s_lshl_b32 s12, s26, 11
	s_add_u32 s12, s30, s12
	s_addc_u32 s13, s31, 0
	s_add_u32 s12, s12, 0x1d00000
	s_addc_u32 s13, s13, 0
	v_mul_f32_e32 v120, v13, v120
	v_mul_f32_e32 v121, v13, v121
	v_mul_f32_e32 v122, v13, v122
	v_mul_f32_e32 v123, v13, v123
	v_mul_f32_e32 v124, v13, v124
	v_mul_f32_e32 v125, v13, v125
	v_mul_f32_e32 v126, v13, v126
	v_mul_f32_e32 v127, v13, v127
	v_mul_f32_e32 v128, v13, v128
	v_mul_f32_e32 v129, v13, v129
	v_mul_f32_e32 v130, v13, v130
	v_mul_f32_e32 v131, v13, v131
	v_mul_f32_e32 v132, v13, v132
	v_mul_f32_e32 v133, v13, v133
	v_mul_f32_e32 v134, v13, v134
	v_mul_f32_e32 v135, v13, v135
	v_mul_f32_e32 v120, v16, v120
	v_mul_f32_e32 v121, v17, v121
	v_mul_f32_e32 v122, v18, v122
	v_mul_f32_e32 v123, v19, v123
	v_mul_f32_e32 v124, v20, v124
	v_mul_f32_e32 v125, v21, v125
	v_mul_f32_e32 v126, v22, v126
	v_mul_f32_e32 v127, v23, v127
	v_mul_f32_e32 v128, v24, v128
	v_mul_f32_e32 v129, v25, v129
	v_mul_f32_e32 v130, v26, v130
	v_mul_f32_e32 v131, v27, v131
	v_mul_f32_e32 v132, v28, v132
	v_mul_f32_e32 v133, v29, v133
	v_mul_f32_e32 v134, v30, v134
	v_mul_f32_e32 v135, v31, v135
	v_fma_f32 v120, v64, v120, v80
	v_fma_f32 v121, v65, v121, v81
	v_fma_f32 v122, v66, v122, v82
	v_fma_f32 v123, v67, v123, v83
	v_fma_f32 v124, v68, v124, v84
	v_fma_f32 v125, v69, v125, v85
	v_fma_f32 v126, v70, v126, v86
	v_fma_f32 v127, v71, v127, v87
	v_fma_f32 v128, v72, v128, v88
	v_fma_f32 v129, v73, v129, v89
	v_fma_f32 v130, v74, v130, v90
	v_fma_f32 v131, v75, v131, v91
	v_fma_f32 v132, v76, v132, v92
	v_fma_f32 v133, v77, v133, v93
	v_fma_f32 v134, v78, v134, v94
	v_fma_f32 v135, v79, v135, v95
	v_cvt_pk_bf16_f32 v120, v120, v121
	v_cvt_pk_bf16_f32 v121, v122, v123
	v_cvt_pk_bf16_f32 v122, v124, v125
	v_cvt_pk_bf16_f32 v123, v126, v127
	v_cvt_pk_bf16_f32 v124, v128, v129
	v_cvt_pk_bf16_f32 v125, v130, v131
	v_cvt_pk_bf16_f32 v126, v132, v133
	v_cvt_pk_bf16_f32 v127, v134, v135
	global_store_dwordx4 v0, v[120:123], s[12:13]
	global_store_dwordx4 v0, v[124:127], s[12:13] offset:1024
	s_add_i32 s26, s26, s88
	s_cmpk_gt_i32 s26, 0x7fff
	s_cbranch_scc1 .Lp6_done
	s_branch .Lp6_e0
